# rebalance: sample-scan split 0x2200 units on the scan half (was 0x3000) after the retention half got faster
# speedup vs baseline: 1.0093x; 1.0014x over previous
.LBB0_740:
	v_readlane_b32 s90, v244, 3
	v_readlane_b32 s62, v244, 0
	v_readlane_b32 s58, v245, 58
	v_readlane_b32 s56, v245, 60
	s_bitcmp0_b32 s82, 4
	v_readlane_b32 s88, v244, 7
	v_readlane_b32 s91, v244, 4
	v_readlane_b32 s61, v244, 2
	v_readlane_b32 s63, v244, 1
	v_readlane_b32 s59, v245, 59
	v_readlane_b32 s57, v245, 61
	v_readlane_b32 s60, v244, 8
	s_cbranch_scc1 .LBB0_762
	s_lshl_b32 s0, s92, 3
	s_add_i32 s10, s84, s0
	s_addk_i32 s10, 0x2200
	s_cmpk_gt_i32 s10, 0x7fff
	s_cbranch_scc1 .LBB0_762
	s_add_u32 s0, s96, 0xe800000
	s_addc_u32 s1, s97, 0
	s_add_u32 s8, s96, 0x10a40000
	s_addc_u32 s9, s97, 0
	v_readlane_b32 s12, v245, 6
	s_add_u32 s2, s96, 0x2f00000
	v_readlane_b32 s20, v245, 14
	s_addc_u32 s3, s97, 0
	v_readlane_b32 s13, v245, 7
	v_readlane_b32 s14, v245, 8
	v_readlane_b32 s15, v245, 9
	v_readlane_b32 s21, v245, 15
	s_add_u32 s20, s96, 0x17100000
	v_and_b32_e32 v2, 15, v208
	v_readlane_b32 s23, v245, 17
	s_addc_u32 s21, s97, 0
	v_readlane_b32 s12, v245, 0
	s_lshl_b32 s11, s60, 3
	v_mov_b32_e32 v1, 0
	v_lshlrev_b32_e32 v0, 4, v2
	v_readlane_b32 s18, v245, 12
	v_readlane_b32 s19, v245, 13
	v_readlane_b32 s13, v245, 1
	v_readlane_b32 s14, v245, 2
	v_readlane_b32 s15, v245, 3
	s_sub_i32 s23, 0, s11
	s_lshl_b32 s11, s88, 3
	v_readlane_b32 s24, v245, 18
	s_waitcnt vmcnt(0)
	v_lshl_add_u64 v[18:19], s[18:19], 0, v[0:1]
	v_lshl_add_u64 v[0:1], s[14:15], 0, v[0:1]
	s_mov_b64 s[12:13], 0x4ab1200
	s_add_i32 s11, s84, s11
	v_readlane_b32 s25, v245, 19
	v_readlane_b32 s26, v245, 20
	v_lshl_add_u64 v[20:21], v[0:1], 0, s[12:13]
	s_add_i32 s24, s11, 0x2200
	s_lshl_b32 s11, s33, 3
	s_lshl_b32 s12, s60, 4
	v_readlane_b32 s22, v245, 16
	v_readlane_b32 s27, v245, 21
	s_sub_i32 s25, s11, s12
	s_lshl_b32 s26, s10, 2
	s_lshl_b32 s10, s33, 6
	s_lshl_b32 s11, s60, 6
	v_lshrrev_b32_e32 v17, 4, v179
	v_lshlrev_b32_e32 v16, 2, v2
	v_cmp_ne_u32_e64 s[4:5], 0, v2
	v_cmp_eq_u32_e64 s[6:7], 0, v2
	s_lshl_b32 s22, s76, 4
	s_sub_i32 s27, s10, s11
	v_readlane_b32 s16, v245, 10
	v_readlane_b32 s17, v245, 11
	s_branch .LBB0_744

.LBB0_798:
	s_bitcmp0_b32 s82, 4
	s_cbranch_scc1 .LBB0_820
	s_lshl_b32 s0, s88, 3
	s_add_i32 s2, s84, s0
	s_cmp_gt_i32 s2, 0x21ff
	s_cbranch_scc1 .LBB0_820
	v_readlane_b32 s4, v245, 6
	s_lshl_b32 s3, s60, 3
	v_readlane_b32 s6, v245, 8
	v_readlane_b32 s7, v245, 9
	s_add_u32 s6, s96, 0xe800000
	v_readlane_b32 s8, v245, 10
	s_addc_u32 s7, s97, 0
	v_readlane_b32 s9, v245, 11
	s_add_u32 s8, s96, 0x10a40000
	v_readlane_b32 s12, v245, 14
	v_readlane_b32 s13, v245, 15
	v_readlane_b32 s14, v245, 16
	v_readlane_b32 s15, v245, 17
	s_addc_u32 s9, s97, 0
	s_add_u32 s20, s96, 0x2f00000
	v_readlane_b32 s12, v245, 0
	s_waitcnt vmcnt(5)
	v_mov_b32_e32 v1, 0
	v_lshlrev_b32_e32 v0, 4, v70
	v_readlane_b32 s10, v245, 12
	v_readlane_b32 s11, v245, 13
	s_addc_u32 s21, s97, 0
	v_readlane_b32 s14, v245, 2
	v_readlane_b32 s15, v245, 3
	v_lshl_add_u64 v[18:19], s[10:11], 0, v[0:1]
	s_add_u32 s22, s96, 0x17100000
	v_lshl_add_u64 v[0:1], s[14:15], 0, v[0:1]
	s_mov_b64 s[10:11], 0x4ab1200
	v_readlane_b32 s5, v245, 7
	s_addc_u32 s23, s97, 0
	s_waitcnt vmcnt(4)
	v_lshl_add_u64 v[20:21], v[0:1], 0, s[10:11]
	s_lshl_b32 s10, s88, 5
	s_lshl_b32 s11, s84, 2
	v_lshlrev_b32_e32 v16, 2, v70
	v_cmp_ne_u32_e64 s[0:1], 0, v70
	v_cmp_eq_u32_e64 s[4:5], 0, v70
	s_lshl_b32 s24, s60, 4
	s_add_i32 s25, s10, s11
	s_lshl_b32 s26, s60, 6
	v_readlane_b32 s16, v245, 18
	v_readlane_b32 s17, v245, 19
	v_readlane_b32 s18, v245, 20
	v_readlane_b32 s19, v245, 21
	v_readlane_b32 s13, v245, 1
	s_branch .LBB0_802
.LBB0_801:
	s_add_i32 s2, s2, s24
	s_add_i32 s25, s25, s26
	s_cmp_gt_i32 s2, 0x21ff
	s_cbranch_scc1 .LBB0_820
.LBB0_802:
	s_ashr_i32 s29, s2, 8
	s_lshl_b32 s10, s29, 10
	s_and_b32 s28, s25, 0x3c0
	v_readlane_b32 s36, v245, 6
	s_or_b32 s34, s28, s10
	s_mul_i32 s11, s29, 0x3480
	v_readlane_b32 s40, v245, 10
	s_mul_hi_i32 s10, s29, 0x3480
	v_readlane_b32 s41, v245, 11
	s_add_u32 s14, s40, s11
	s_addc_u32 s15, s41, s10
	s_add_i32 s18, s3, s2
	s_cmp_lt_i32 s18, 0x2200
	s_cselect_b64 s[10:11], -1, 0
	s_cmp_gt_i32 s18, 0x21ff
	s_cselect_b64 s[12:13], -1, 0
	s_and_b64 s[16:17], s[12:13], exec
	s_cselect_b32 s16, s2, s18
	s_ashr_i32 s35, s16, 8
	s_lshl_b32 s36, s16, 2
	v_readlane_b32 s37, v245, 7
	s_lshl_b32 s16, s35, 10
	s_and_b32 s27, s36, 0x3c0
	s_or_b32 s37, s27, s16
	s_mul_i32 s17, s35, 0x3480
	s_mul_hi_i32 s16, s35, 0x3480
	s_add_u32 s18, s40, s17
	s_addc_u32 s19, s41, s16
	s_lshl_b32 s29, s29, 2
	s_add_i32 s16, s29, 0x2040
	s_ashr_i32 s17, s16, 31
	s_lshl_b64 s[30:31], s[16:17], 10
	s_or_b32 s30, s30, s28
	v_mov_b32_e32 v5, s31
	v_or_b32_e32 v4, s30, v16
	v_lshl_add_u64 v[0:1], v[4:5], 3, s[8:9]
	v_and_or_b32 v29, s25, 60, v61
	global_load_dwordx4 v[38:41], v[0:1], off
	global_load_dwordx4 v[42:45], v[0:1], off offset:16
	v_or_b32_e32 v0, s34, v29
	v_ashrrev_i32_e32 v1, 31, v0
	v_readlane_b32 s42, v245, 12
	v_readlane_b32 s43, v245, 13
	v_readlane_b32 s44, v245, 14
	v_readlane_b32 s45, v245, 15
	v_readlane_b32 s46, v245, 16
	v_readlane_b32 s47, v245, 17
	v_readlane_b32 s48, v245, 18
	v_readlane_b32 s49, v245, 19
	v_readlane_b32 s50, v245, 20
	v_readlane_b32 s51, v245, 21
	v_lshlrev_b64 v[22:23], 8, v[0:1]
	v_or_b32_e32 v0, s28, v29
	v_or_b32_e32 v0, 0x800, v0
	s_mul_i32 s30, s16, 0x3480
	v_readlane_b32 s40, v245, 22
	v_lshlrev_b32_e32 v27, 2, v0
	s_mul_hi_i32 s31, s16, 0x3480
	s_add_u32 s30, s20, s30
	v_readlane_b32 s41, v245, 23
	s_addc_u32 s31, s21, s31
	s_nop 3
	global_load_dword v26, v27, s[40:41]
	global_load_dword v33, v27, s[14:15]
	global_load_dword v32, v27, s[30:31]
	s_lshl_b32 s30, s35, 2
	s_add_i32 s14, s30, 0x2040
	v_lshl_add_u64 v[0:1], v[18:19], 0, v[22:23]
	v_and_or_b32 v30, s36, 60, v61
	s_ashr_i32 s15, s14, 31
	global_load_dwordx4 v[46:49], v[0:1], off
	v_or_b32_e32 v0, s37, v30
	s_lshl_b64 s[34:35], s[14:15], 10
	v_ashrrev_i32_e32 v1, 31, v0
	v_or_b32_e32 v6, s27, v30
	v_lshl_add_u64 v[4:5], v[4:5], 2, s[6:7]
	s_or_b32 s31, s34, s27
	v_lshlrev_b64 v[24:25], 8, v[0:1]
	v_or_b32_e32 v6, 0x800, v6
	global_load_dwordx4 v[50:53], v[4:5], off
	v_mov_b32_e32 v5, s35
	v_or_b32_e32 v4, s31, v16
	s_mul_i32 s34, s14, 0x3480
	v_lshl_add_u64 v[0:1], v[18:19], 0, v[24:25]
	v_lshlrev_b32_e32 v28, 2, v6
	v_lshl_add_u64 v[6:7], v[4:5], 2, s[6:7]
	v_lshl_add_u64 v[12:13], v[4:5], 3, s[8:9]
	s_mul_hi_i32 s31, s14, 0x3480
	s_add_u32 s34, s20, s34
	global_load_dwordx4 v[0:3], v[0:1], off
	s_nop 0
	global_load_dwordx4 v[8:11], v[12:13], off offset:16
	s_nop 0
	global_load_dwordx4 v[4:7], v[6:7], off
	s_nop 0
	global_load_dwordx4 v[12:15], v[12:13], off
	s_addc_u32 s35, s21, s31
	global_load_dword v17, v28, s[40:41]
	global_load_dword v37, v28, s[18:19]
	global_load_dword v31, v28, s[34:35]
	s_add_i32 s64, s29, 0x2041
	s_ashr_i32 s65, s64, 31
	s_lshl_b64 s[66:67], s[64:65], 10
	v_mov_b32_e32 v236, s28
	v_or3_b32 v236, s66, v236, v16
	v_or3_b32 v237, s67, 0, 0
	s_mul_hi_i32 s67, s64, 0x3480
	s_mul_i32 s66, s64, 0x3480
	s_add_u32 s66, s20, s66
	s_addc_u32 s67, s21, s67
	v_lshl_add_u64 v[238:239], v[236:237], 3, s[8:9]
	global_load_dwordx4 v[148:151], v[238:239], off
	global_load_dwordx4 v[152:155], v[238:239], off offset:16
	global_load_dword v172, v27, s[66:67]
	v_lshl_add_u64 v[238:239], v[236:237], 2, s[6:7]
	global_load_dwordx4 v[156:159], v[238:239], off
	s_add_i32 s64, s30, 0x2041
	s_ashr_i32 s65, s64, 31
	s_lshl_b64 s[66:67], s[64:65], 10
	v_mov_b32_e32 v236, s27
	v_or3_b32 v236, s66, v236, v16
	v_or3_b32 v237, s67, 0, 0
	s_mul_hi_i32 s67, s64, 0x3480
	s_mul_i32 s66, s64, 0x3480
	s_add_u32 s66, s20, s66
	s_addc_u32 s67, s21, s67
	v_lshl_add_u64 v[238:239], v[236:237], 3, s[8:9]
	global_load_dwordx4 v[160:163], v[238:239], off
	global_load_dwordx4 v[164:167], v[238:239], off offset:16
	global_load_dword v173, v28, s[66:67]
	v_lshl_add_u64 v[238:239], v[236:237], 2, s[6:7]
	global_load_dwordx4 v[168:171], v[238:239], off
	s_add_i32 s64, s29, 0x2042
	s_ashr_i32 s65, s64, 31
	s_lshl_b64 s[66:67], s[64:65], 10
	v_mov_b32_e32 v236, s28
	v_or3_b32 v236, s66, v236, v16
	v_or3_b32 v237, s67, 0, 0
	s_mul_hi_i32 s67, s64, 0x3480
	s_mul_i32 s66, s64, 0x3480
	s_add_u32 s66, s20, s66
	s_addc_u32 s67, s21, s67
	v_lshl_add_u64 v[238:239], v[236:237], 3, s[8:9]
	global_load_dwordx4 v[180:183], v[238:239], off
	global_load_dwordx4 v[184:187], v[238:239], off offset:16
	global_load_dword v204, v27, s[66:67]
	v_lshl_add_u64 v[238:239], v[236:237], 2, s[6:7]
	global_load_dwordx4 v[188:191], v[238:239], off
	s_add_i32 s64, s30, 0x2042
	s_ashr_i32 s65, s64, 31
	s_lshl_b64 s[66:67], s[64:65], 10
	v_mov_b32_e32 v236, s27
	v_or3_b32 v236, s66, v236, v16
	v_or3_b32 v237, s67, 0, 0
	s_mul_hi_i32 s67, s64, 0x3480
	s_mul_i32 s66, s64, 0x3480
	s_add_u32 s66, s20, s66
	s_addc_u32 s67, s21, s67
	v_lshl_add_u64 v[238:239], v[236:237], 3, s[8:9]
	global_load_dwordx4 v[192:195], v[238:239], off
	global_load_dwordx4 v[196:199], v[238:239], off offset:16
	global_load_dword v205, v28, s[66:67]
	v_lshl_add_u64 v[238:239], v[236:237], 2, s[6:7]
	global_load_dwordx4 v[200:203], v[238:239], off
	s_add_i32 s64, s29, 0x2043
	s_ashr_i32 s65, s64, 31
	s_lshl_b64 s[66:67], s[64:65], 10
	v_mov_b32_e32 v236, s28
	v_or3_b32 v236, s66, v236, v16
	v_or3_b32 v237, s67, 0, 0
	s_mul_hi_i32 s67, s64, 0x3480
	s_mul_i32 s66, s64, 0x3480
	s_add_u32 s66, s20, s66
	s_addc_u32 s67, s21, s67
	v_lshl_add_u64 v[238:239], v[236:237], 3, s[8:9]
	global_load_dwordx4 v[210:213], v[238:239], off
	global_load_dwordx4 v[214:217], v[238:239], off offset:16
	global_load_dword v234, v27, s[66:67]
	v_lshl_add_u64 v[238:239], v[236:237], 2, s[6:7]
	global_load_dwordx4 v[218:221], v[238:239], off
	s_add_i32 s64, s30, 0x2043
	s_ashr_i32 s65, s64, 31
	s_lshl_b64 s[66:67], s[64:65], 10
	v_mov_b32_e32 v236, s27
	v_or3_b32 v236, s66, v236, v16
	v_or3_b32 v237, s67, 0, 0
	s_mul_hi_i32 s67, s64, 0x3480
	s_mul_i32 s66, s64, 0x3480
	s_add_u32 s66, s20, s66
	s_addc_u32 s67, s21, s67
	v_lshl_add_u64 v[238:239], v[236:237], 3, s[8:9]
	global_load_dwordx4 v[222:225], v[238:239], off
	global_load_dwordx4 v[226:229], v[238:239], off offset:16
	global_load_dword v235, v28, s[66:67]
	v_lshl_add_u64 v[238:239], v[236:237], 2, s[6:7]
	global_load_dwordx4 v[230:233], v[238:239], off
	v_lshlrev_b32_e32 v29, 2, v29
	v_readlane_b32 s38, v245, 8
	v_readlane_b32 s39, v245, 9
	v_readlane_b32 s42, v245, 24
	v_readlane_b32 s43, v245, 25
	v_readlane_b32 s44, v245, 26
	v_readlane_b32 s45, v245, 27
	v_readlane_b32 s46, v245, 28
	v_readlane_b32 s47, v245, 29
	v_readlane_b32 s48, v245, 30
	v_readlane_b32 s49, v245, 31
	v_readlane_b32 s50, v245, 32
	v_readlane_b32 s51, v245, 33
	v_readlane_b32 s52, v245, 34
	v_readlane_b32 s53, v245, 35
	v_readlane_b32 s54, v245, 36
	v_readlane_b32 s55, v245, 37
	s_waitcnt vmcnt(37)
	v_lshlrev_b32_e32 v55, 16, v40
	v_and_b32_e32 v35, 0xffff0000, v40
	v_lshlrev_b32_e32 v40, 16, v39
	v_lshlrev_b32_e32 v54, 16, v38
	s_waitcnt vmcnt(36)
	v_lshlrev_b32_e32 v56, 16, v42
	v_lshlrev_b32_e32 v57, 16, v44
	v_and_b32_e32 v34, 0xffff0000, v38
	v_and_b32_e32 v36, 0xffff0000, v42
	v_and_b32_e32 v38, 0xffff0000, v44
	v_lshlrev_b32_e32 v42, 16, v41
	v_lshlrev_b32_e32 v44, 16, v43
	v_lshlrev_b32_e32 v58, 16, v45
	v_and_b32_e32 v39, 0xffff0000, v39
	v_and_b32_e32 v41, 0xffff0000, v41
	v_and_b32_e32 v43, 0xffff0000, v43
	v_and_b32_e32 v45, 0xffff0000, v45
	s_waitcnt vmcnt(33)
	v_sub_f32_e32 v33, v33, v32
	v_fma_f32 v59, v26, v33, v32
	s_waitcnt vmcnt(32)
	v_mul_f32 v33, v46, v40
	v_mul_f32 v40, v48, v44
	v_mul_f32 v34, v59, v34
	v_mul_f32 v35, v59, v35
	s_nop 0
	v_fma_f32 v33, v47, v42, v33
	v_fma_f32 v40, v49, v58, v40
	s_nop 0
	v_add_f32 v33, v33, v40
	s_nop 1
	v_add_f32_dpp v33, v33, v33 row_ror:8 row_mask:0xf bank_mask:0xf bound_ctrl:1
	s_nop 1
	v_add_f32_dpp v33, v33, v33 row_ror:4 row_mask:0xf bank_mask:0xf bound_ctrl:1
	s_nop 1
	v_add_f32_dpp v33, v33, v33 row_ror:2 row_mask:0xf bank_mask:0xf bound_ctrl:1
	s_nop 1
	v_add_f32_dpp v40, v33, v33 row_ror:1 row_mask:0xf bank_mask:0xf bound_ctrl:1
	v_fma_f32 v33, v40, v39, v34
	v_fma_f32 v34, v40, v41, v35
	v_mul_f32 v35, v59, v36
	v_mul_f32 v36, v59, v38
	s_waitcnt vmcnt(31)
	v_fma_f32 v33, v46, v50, v33
	v_fma_f32 v35, v40, v43, v35
	v_fma_f32 v34, v47, v51, v34
	v_fma_f32 v36, v40, v45, v36
	s_nop 0
	v_mul_f32 v38, v33, v54
	v_fma_f32 v35, v48, v52, v35
	v_fma_f32 v36, v49, v53, v36
	s_nop 0
	v_fma_f32 v38, v34, v55, v38
	v_mul_f32 v39, v35, v56
	s_nop 0
	v_fma_f32 v39, v36, v57, v39
	s_nop 0
	v_add_f32 v38, v38, v39
	v_mov_b32_e32 v39, 0
	s_nop 0
	v_add_f32_dpp v38, v38, v38 row_ror:8 row_mask:0xf bank_mask:0xf bound_ctrl:1
	s_nop 1
	v_add_f32_dpp v38, v38, v38 row_ror:4 row_mask:0xf bank_mask:0xf bound_ctrl:1
	s_nop 1
	v_add_f32_dpp v38, v38, v38 row_ror:2 row_mask:0xf bank_mask:0xf bound_ctrl:1
	s_nop 1
	v_mov_b32_dpp v39, v38 row_ror:1 row_mask:0xf bank_mask:0xf
	s_and_saveexec_b64 s[18:19], s[4:5]
	s_cbranch_execz .LBB0_804
	s_lshl_b64 s[16:17], s[16:17], 12
	s_add_u32 s16, s22, s16
	s_addc_u32 s17, s23, s17
	s_lshl_b32 s31, s28, 2
	s_add_u32 s16, s16, s31
	s_addc_u32 s17, s17, 0
	v_add_f32_e32 v38, v38, v39
	global_store_dword v29, v38, s[16:17]
